# k06 + attention preamble head sums computed 4-wide (8 loads up front, interleaved xor-reduction)
# baseline (speedup 1.0000x reference)
.LBB0_777:
	v_readlane_b32 s0, v254, 14
	v_readlane_b32 s1, v254, 15
	s_cmp_lt_i32 s0, 8
	v_writelane_b32 v255, s78, 13
	s_cselect_b64 s[0:1], -1, 0
	s_and_b64 s[2:3], s[0:1], s[4:5]
	v_writelane_b32 v255, s79, 14
	v_writelane_b32 v255, s76, 28
	s_andn2_b64 vcc, exec, s[2:3]
	s_nop 0
	v_writelane_b32 v255, s77, 29
	s_cbranch_vccnz .LBB0_846
	v_writelane_b32 v255, s2, 32
	v_lshlrev_b32_e32 v2, 2, v1
	v_mbcnt_lo_u32_b32 v4, -1, 0
	v_writelane_b32 v255, s3, 33
	v_readlane_b32 s0, v254, 34
	v_readlane_b32 s4, v254, 38
	v_readlane_b32 s5, v254, 39
	v_readlane_b32 s6, v254, 40
	v_readlane_b32 s7, v254, 41
	s_waitcnt lgkmcnt(0)
	s_nop 1
	global_load_dword v3, v2, s[4:5]
	s_nop 0
	global_load_dword v2, v2, s[6:7]
	v_mbcnt_hi_u32_b32 v4, -1, v4
	v_and_b32_e32 v5, 64, v4
	v_xor_b32_e32 v6, 1, v4
	v_add_u32_e32 v16, 64, v5
	v_cmp_lt_i32_e32 vcc, v6, v16
	v_xor_b32_e32 v7, 2, v4
	v_xor_b32_e32 v8, 4, v4
	v_cndmask_b32_e32 v6, v4, v6, vcc
	v_lshlrev_b32_e32 v10, 2, v6
	v_cmp_lt_i32_e32 vcc, v7, v16
	v_xor_b32_e32 v9, 8, v4
	v_xor_b32_e32 v14, 16, v4
	v_cndmask_b32_e32 v7, v4, v7, vcc
	v_cmp_lt_i32_e32 vcc, v8, v16
	v_xor_b32_e32 v15, 32, v4
	v_readlane_b32 s1, v254, 35
	v_cndmask_b32_e32 v8, v4, v8, vcc
	v_cmp_lt_i32_e32 vcc, v9, v16
	v_readlane_b32 s0, v254, 56
	s_add_u32 s24, s72, 0x9310000
	v_readlane_b32 s1, v254, 57
	s_addc_u32 s25, s73, 0
	s_mov_b32 s27, 0
	v_readlane_b32 s2, v254, 36
	v_readlane_b32 s3, v254, 37
	v_readlane_b32 s8, v254, 42
	v_readlane_b32 s9, v254, 43
	v_readlane_b32 s10, v254, 44
	v_readlane_b32 s11, v254, 45
	v_readlane_b32 s12, v254, 46
	v_readlane_b32 s13, v254, 47
	v_readlane_b32 s14, v254, 48
	v_readlane_b32 s15, v254, 49
	s_waitcnt vmcnt(1)
	v_and_b32_e32 v6, 0x7fffffff, v3
	s_waitcnt vmcnt(0)
	v_and_b32_e32 v11, 0x7fffffff, v2
	ds_bpermute_b32 v6, v10, v6
	ds_bpermute_b32 v12, v10, v11
	v_lshlrev_b32_e32 v11, 2, v7
	v_max_f32_e64 v3, |v3|, |v3|
	v_max_f32_e64 v2, |v2|, |v2|
	s_waitcnt lgkmcnt(1)
	v_max_f32_e32 v6, v6, v6
	s_waitcnt lgkmcnt(0)
	v_max_f32_e32 v7, v12, v12
	v_max_f32_e32 v3, v3, v6
	v_max_f32_e32 v2, v2, v7
	ds_bpermute_b32 v6, v11, v3
	ds_bpermute_b32 v7, v11, v2
	v_lshlrev_b32_e32 v12, 2, v8
	v_cndmask_b32_e32 v8, v4, v9, vcc
	v_lshlrev_b32_e32 v13, 2, v8
	s_waitcnt lgkmcnt(1)
	v_max_f32_e32 v6, v6, v6
	s_waitcnt lgkmcnt(0)
	v_max_f32_e32 v7, v7, v7
	v_max_f32_e32 v3, v3, v6
	v_max_f32_e32 v2, v2, v7
	ds_bpermute_b32 v6, v12, v3
	ds_bpermute_b32 v7, v12, v2
	v_cmp_lt_i32_e32 vcc, v14, v16
	s_waitcnt lgkmcnt(1)
	v_max_f32_e32 v6, v6, v6
	s_waitcnt lgkmcnt(0)
	v_max_f32_e32 v7, v7, v7
	v_max_f32_e32 v3, v3, v6
	v_max_f32_e32 v2, v2, v7
	ds_bpermute_b32 v6, v13, v3
	ds_bpermute_b32 v7, v13, v2
	v_cndmask_b32_e32 v8, v4, v14, vcc
	v_lshlrev_b32_e32 v14, 2, v8
	v_cmp_lt_i32_e32 vcc, v15, v16
	s_waitcnt lgkmcnt(1)
	v_max_f32_e32 v6, v6, v6
	s_waitcnt lgkmcnt(0)
	v_max_f32_e32 v7, v7, v7
	v_max_f32_e32 v3, v3, v6
	v_max_f32_e32 v2, v2, v7
	ds_bpermute_b32 v6, v14, v3
	ds_bpermute_b32 v7, v14, v2
	v_cndmask_b32_e32 v8, v4, v15, vcc
	v_lshlrev_b32_e32 v15, 2, v8
	s_andn2_b64 vcc, exec, s[0:1]
	s_waitcnt lgkmcnt(1)
	v_max_f32_e32 v6, v6, v6
	s_waitcnt lgkmcnt(0)
	v_max_f32_e32 v8, v7, v7
	v_max_f32_e32 v7, v3, v6
	v_max_f32_e32 v6, v2, v8
	ds_bpermute_b32 v9, v15, v7
	ds_bpermute_b32 v8, v15, v6
	s_cbranch_vccnz .LBB0_790
	v_readlane_b32 s0, v254, 55
	v_mov_b32_e32 v3, 0
	v_cmp_eq_u32_e32 vcc, 0, v1
	v_lshl_or_b32 v2, s0, 9, v1
	v_lshl_add_u64 v[16:17], v[2:3], 2, s[24:25]
	global_load_dword v18, v[16:17], off
	global_load_dword v19, v[16:17], off offset:256
	global_load_dword v20, v[16:17], off offset:512
	global_load_dword v21, v[16:17], off offset:768
	global_load_dword v22, v[16:17], off offset:1024
	global_load_dword v23, v[16:17], off offset:1280
	global_load_dword v24, v[16:17], off offset:1536
	global_load_dword v25, v[16:17], off offset:1792
	s_lshl_b32 s0, s0, 4
	s_add_i32 s0, s0, 0x20000
	s_waitcnt vmcnt(0)
	v_add_f32_e32 v18, v18, v19
	v_add_f32_e32 v20, v20, v21
	v_add_f32_e32 v22, v22, v23
	v_add_f32_e32 v24, v24, v25
	ds_bpermute_b32 v19, v10, v18
	ds_bpermute_b32 v21, v10, v20
	ds_bpermute_b32 v23, v10, v22
	ds_bpermute_b32 v25, v10, v24
	s_waitcnt lgkmcnt(0)
	v_add_f32_e32 v18, v18, v19
	v_add_f32_e32 v20, v20, v21
	v_add_f32_e32 v22, v22, v23
	v_add_f32_e32 v24, v24, v25
	ds_bpermute_b32 v19, v11, v18
	ds_bpermute_b32 v21, v11, v20
	ds_bpermute_b32 v23, v11, v22
	ds_bpermute_b32 v25, v11, v24
	s_waitcnt lgkmcnt(0)
	v_add_f32_e32 v18, v18, v19
	v_add_f32_e32 v20, v20, v21
	v_add_f32_e32 v22, v22, v23
	v_add_f32_e32 v24, v24, v25
	ds_bpermute_b32 v19, v12, v18
	ds_bpermute_b32 v21, v12, v20
	ds_bpermute_b32 v23, v12, v22
	ds_bpermute_b32 v25, v12, v24
	s_waitcnt lgkmcnt(0)
	v_add_f32_e32 v18, v18, v19
	v_add_f32_e32 v20, v20, v21
	v_add_f32_e32 v22, v22, v23
	v_add_f32_e32 v24, v24, v25
	ds_bpermute_b32 v19, v13, v18
	ds_bpermute_b32 v21, v13, v20
	ds_bpermute_b32 v23, v13, v22
	ds_bpermute_b32 v25, v13, v24
	s_waitcnt lgkmcnt(0)
	v_add_f32_e32 v18, v18, v19
	v_add_f32_e32 v20, v20, v21
	v_add_f32_e32 v22, v22, v23
	v_add_f32_e32 v24, v24, v25
	ds_bpermute_b32 v19, v14, v18
	ds_bpermute_b32 v21, v14, v20
	ds_bpermute_b32 v23, v14, v22
	ds_bpermute_b32 v25, v14, v24
	s_waitcnt lgkmcnt(0)
	v_add_f32_e32 v18, v18, v19
	v_add_f32_e32 v20, v20, v21
	v_add_f32_e32 v22, v22, v23
	v_add_f32_e32 v24, v24, v25
	ds_bpermute_b32 v19, v15, v18
	ds_bpermute_b32 v21, v15, v20
	ds_bpermute_b32 v23, v15, v22
	ds_bpermute_b32 v25, v15, v24
	s_waitcnt lgkmcnt(0)
	v_add_f32_e32 v18, v18, v19
	v_add_f32_e32 v20, v20, v21
	v_add_f32_e32 v22, v22, v23
	v_add_f32_e32 v24, v24, v25
	s_and_saveexec_b64 s[2:3], vcc
	v_mov_b32_e32 v16, s0
	ds_write2_b32 v16, v18, v20 offset1:1
	ds_write2_b32 v16, v22, v24 offset0:2 offset1:3
